# ctx-DFT epilogue: first column group's read-modify-write loads also batched (addresses precomputed into spare registers)
# baseline (speedup 1.0000x reference)
; #define PG8_STAGE(bufoff, gbase, voff) do { _Pragma("unroll") for (int _i = 0; _i < 2; ++_i) \
;         __builtin_amdgcn_global_load_lds((const unsigned*)((const char*)(gbase) + (voff)[_i]), (LAS unsigned*)(lds + (bufoff) + ldsw + _i * 8192), 16, 0, 0); } while (0)
; #define PG8_WAIT_V(n) asm volatile("s_waitcnt vmcnt(" #n ")" ::: "memory")
; #define PG8_BAR __builtin_amdgcn_s_barrier()
; template <class Epi, class Sched>
; __device__ __forceinline__ void gemm_phase(LAS unsigned char* lds, const int K, const int lda, const int ldb, const Sched& S, const Epi& E) {
;     ...
;         for (int t = 0; t < nt; t += 2) {
;             const bool last = (t == nt - 2);
;             const char* a1 = cA + (size_t)(t + 1) * kstep;
;             const char* a2 = last ? nA : cA + (size_t)(t + 2) * kstep; const char* b2 = last ? nB : cB + (size_t)(t + 2) * kstep;
;             const char* a3 = a2 + kstep; const char* b3 = b2 + kstep;
;             PG8_LDB(B0, 0, 0); PG8_SCHED; PG8_LDA(At, 0, 0); PG8_STAGE_A(PG8_SA(1, 1), a1, 1, vcur);
;             if constexpr (GATHER) { if (last) {
; #pragma unroll
;                 for (int h = 0; h < 2; ++h)
; #pragma unroll
;                     for (int i = 0; i < 2; ++i) vcur[h][i] = vnxt[h][i]; } }
;             PG8_WAIT_L(8); PG8_BAR; PG8_WAIT_L(0); PG8_MMA(0, 0, At, B0); PG8_BAR; PG8_SCHED;
;             PG8_LDB(B1, 0, 1); PG8_STAGE(PG8_SB(0, 0), b2, voffB);
;             PG8_BAR; PG8_WAIT_L(0); PG8_MMA(0, 1, At, B1); PG8_BAR;
;             PG8_LDA(At, 0, 1); PG8_STAGE_A(PG8_SA(0, 0), a2, 0, vcur);
;             PG8_BAR; PG8_WAIT_L(0); PG8_MMA(1, 0, At, B0); PG8_BAR; PG8_SCHED;
;             PG8_STAGE(PG8_SB(0, 1), b2 + hstepB, voffB);
;             PG8_WAIT_V(6); PG8_BAR; PG8_MMA(1, 1, At, B1); PG8_BAR;
;             PG8_LDB(B0, 1, 0); PG8_SCHED; PG8_LDA(At, 1, 0); PG8_STAGE_A(PG8_SA(0, 1), a2, 1, vcur);
;             PG8_WAIT_L(8); PG8_BAR; PG8_WAIT_L(0); PG8_MMA(0, 0, At, B0); PG8_BAR; PG8_SCHED;
;             PG8_LDB(B1, 1, 1); PG8_STAGE(PG8_SB(1, 0), b3, voffB);
;             PG8_BAR; PG8_WAIT_L(0); PG8_MMA(0, 1, At, B1); PG8_BAR;
;             PG8_LDA(At, 1, 1); PG8_STAGE_A(PG8_SA(1, 0), a3, 0, vcur);
;             PG8_BAR; PG8_WAIT_L(0); PG8_MMA(1, 0, At, B0); PG8_BAR; PG8_SCHED;
;             PG8_STAGE(PG8_SB(1, 1), b3 + hstepB, voffB);
;             PG8_WAIT_V(6); PG8_BAR; PG8_MMA(1, 1, At, B1); PG8_BAR;
.LBB0_270:
	s_add_u32 s2, s10, 0xfffe0080
	s_addc_u32 s3, s11, -1
	s_add_i32 s20, 0, 0x10000
	v_add_u32_e32 v163, s20, v160
	ds_read_b128 v[152:155], v163
	ds_read_b128 v[156:159], v163 offset:1024
	ds_read_b128 v[164:167], v163 offset:2048
	ds_read_b128 v[168:171], v163 offset:3072
	s_cmp_eq_u32 s43, 4
	s_cselect_b32 s15, s7, s3
	s_cselect_b32 s14, s6, s2
	s_cselect_b32 s13, s9, s42
	s_cselect_b32 s12, s8, s41
	v_lshl_add_u64 v[214:215], s[10:11], 0, v[148:149]
	s_add_i32 m0, s19, 0xc000
	ds_read_b128 v[172:175], v162
	ds_read_b128 v[176:179], v162 offset:1024
	ds_read_b128 v[180:183], v162 offset:2048
	ds_read_b128 v[184:187], v162 offset:3072
	ds_read_b128 v[188:191], v162 offset:4096
	ds_read_b128 v[192:195], v162 offset:5120
	ds_read_b128 v[216:219], v162 offset:6144
	ds_read_b128 v[220:223], v162 offset:7168
	global_load_lds_dwordx4 v[214:215], off
	v_lshl_add_u64 v[214:215], s[10:11], 0, v[150:151]
	s_add_i32 m0, s19, 0xe000
	s_nop 0
	global_load_lds_dwordx4 v[214:215], off
	s_waitcnt lgkmcnt(8)
	s_barrier
	s_waitcnt lgkmcnt(0)
	s_setprio 1
	s_waitcnt lgkmcnt(0)
	v_mfma_f32_16x16x32_bf16 v[126:129], v[152:155], v[172:175], v[126:129]
	v_mfma_f32_16x16x32_bf16 v[98:101], v[164:167], v[172:175], v[98:101]
	v_mfma_f32_16x16x32_bf16 v[122:125], v[152:155], v[180:183], v[122:125]
	v_mfma_f32_16x16x32_bf16 v[90:93], v[164:167], v[180:183], v[90:93]
	v_mfma_f32_16x16x32_bf16 v[118:121], v[152:155], v[188:191], v[118:121]
	v_mfma_f32_16x16x32_bf16 v[86:89], v[164:167], v[188:191], v[86:89]
	v_mfma_f32_16x16x32_bf16 v[114:117], v[152:155], v[216:219], v[114:117]
	v_mfma_f32_16x16x32_bf16 v[82:85], v[164:167], v[216:219], v[82:85]
	v_mfma_f32_16x16x32_bf16 v[126:129], v[156:159], v[176:179], v[126:129]
	v_mfma_f32_16x16x32_bf16 v[98:101], v[168:171], v[176:179], v[98:101]
	v_mfma_f32_16x16x32_bf16 v[122:125], v[156:159], v[184:187], v[122:125]
	v_mfma_f32_16x16x32_bf16 v[90:93], v[168:171], v[184:187], v[90:93]
	v_mfma_f32_16x16x32_bf16 v[118:121], v[156:159], v[192:195], v[118:121]
	v_mfma_f32_16x16x32_bf16 v[86:89], v[168:171], v[192:195], v[86:89]
	v_mfma_f32_16x16x32_bf16 v[114:117], v[156:159], v[220:223], v[114:117]
	v_mfma_f32_16x16x32_bf16 v[82:85], v[168:171], v[220:223], v[82:85]
	s_setprio 0
	s_barrier
	s_add_i32 s2, 0, 0x14000
	s_add_i32 s3, s20, s18
	v_add_u32_e32 v163, s2, v160
	v_lshl_add_u64 v[214:215], s[12:13], 0, v[0:1]
	s_mov_b32 m0, s3
	ds_read_b128 v[224:227], v163
	ds_read_b128 v[228:231], v163 offset:1024
	ds_read_b128 v[232:235], v163 offset:2048
	ds_read_b128 v[236:239], v163 offset:3072
	global_load_lds_dwordx4 v[214:215], off
	v_lshl_add_u64 v[240:241], s[12:13], 0, v[130:131]
	s_add_i32 m0, s3, 0x2000
	s_nop 0
	global_load_lds_dwordx4 v[240:241], off
	s_barrier
	s_waitcnt lgkmcnt(0)
	s_setprio 1
	s_waitcnt lgkmcnt(0)
	v_mfma_f32_16x16x32_bf16 v[66:69], v[224:227], v[172:175], v[66:69]
	v_mfma_f32_16x16x32_bf16 v[34:37], v[232:235], v[172:175], v[34:37]
	v_mfma_f32_16x16x32_bf16 v[58:61], v[224:227], v[180:183], v[58:61]
	v_mfma_f32_16x16x32_bf16 v[26:29], v[232:235], v[180:183], v[26:29]
	v_mfma_f32_16x16x32_bf16 v[54:57], v[224:227], v[188:191], v[54:57]
	v_mfma_f32_16x16x32_bf16 v[22:25], v[232:235], v[188:191], v[22:25]
	v_mfma_f32_16x16x32_bf16 v[50:53], v[224:227], v[216:219], v[50:53]
	v_mfma_f32_16x16x32_bf16 v[18:21], v[232:235], v[216:219], v[18:21]
	v_mfma_f32_16x16x32_bf16 v[66:69], v[228:231], v[176:179], v[66:69]
	v_mfma_f32_16x16x32_bf16 v[34:37], v[236:239], v[176:179], v[34:37]
	v_mfma_f32_16x16x32_bf16 v[58:61], v[228:231], v[184:187], v[58:61]
	v_mfma_f32_16x16x32_bf16 v[26:29], v[236:239], v[184:187], v[26:29]
	v_mfma_f32_16x16x32_bf16 v[54:57], v[228:231], v[192:195], v[54:57]
	v_mfma_f32_16x16x32_bf16 v[22:25], v[236:239], v[192:195], v[22:25]
	v_mfma_f32_16x16x32_bf16 v[50:53], v[228:231], v[220:223], v[50:53]
	v_mfma_f32_16x16x32_bf16 v[18:21], v[236:239], v[220:223], v[18:21]
	s_setprio 0
	s_mov_b32 m0, s19
	v_lshl_add_u64 v[242:243], s[14:15], 0, v[0:1]
	s_barrier
	ds_read_b128 v[172:175], v162 offset:16384
	ds_read_b128 v[176:179], v162 offset:17408
	ds_read_b128 v[180:183], v162 offset:18432
	ds_read_b128 v[184:187], v162 offset:19456
	ds_read_b128 v[188:191], v162 offset:20480
	ds_read_b128 v[192:195], v162 offset:21504
	ds_read_b128 v[216:219], v162 offset:22528
	ds_read_b128 v[220:223], v162 offset:23552
	global_load_lds_dwordx4 v[242:243], off
	v_lshl_add_u64 v[244:245], s[14:15], 0, v[130:131]
	s_mov_b32 m0, s30
	s_nop 0
	global_load_lds_dwordx4 v[244:245], off
	s_barrier
	s_waitcnt lgkmcnt(0)
	s_setprio 1
	s_waitcnt lgkmcnt(0)
	v_mfma_f32_16x16x32_bf16 v[110:113], v[152:155], v[172:175], v[110:113]
	v_mfma_f32_16x16x32_bf16 v[78:81], v[164:167], v[172:175], v[78:81]
	v_mfma_f32_16x16x32_bf16 v[106:109], v[152:155], v[180:183], v[106:109]
	v_mfma_f32_16x16x32_bf16 v[74:77], v[164:167], v[180:183], v[74:77]
	v_mfma_f32_16x16x32_bf16 v[102:105], v[152:155], v[188:191], v[102:105]
	v_mfma_f32_16x16x32_bf16 v[70:73], v[164:167], v[188:191], v[70:73]
	v_mfma_f32_16x16x32_bf16 v[94:97], v[152:155], v[216:219], v[94:97]
	v_mfma_f32_16x16x32_bf16 v[62:65], v[164:167], v[216:219], v[62:65]
	v_mfma_f32_16x16x32_bf16 v[110:113], v[156:159], v[176:179], v[110:113]
	v_mfma_f32_16x16x32_bf16 v[78:81], v[168:171], v[176:179], v[78:81]
	v_mfma_f32_16x16x32_bf16 v[106:109], v[156:159], v[184:187], v[106:109]
	v_mfma_f32_16x16x32_bf16 v[74:77], v[168:171], v[184:187], v[74:77]
	v_mfma_f32_16x16x32_bf16 v[102:105], v[156:159], v[192:195], v[102:105]
	v_mfma_f32_16x16x32_bf16 v[70:73], v[168:171], v[192:195], v[70:73]
	v_mfma_f32_16x16x32_bf16 v[94:97], v[156:159], v[220:223], v[94:97]
	v_mfma_f32_16x16x32_bf16 v[62:65], v[168:171], v[220:223], v[62:65]
	s_setprio 0
	s_barrier
; #define PG8_STAGE(bufoff, gbase, voff) do { _Pragma("unroll") for (int _i = 0; _i < 2; ++_i) \
;         __builtin_amdgcn_global_load_lds((const unsigned*)((const char*)(gbase) + (voff)[_i]), (LAS unsigned*)(lds + (bufoff) + ldsw + _i * 8192), 16, 0, 0); } while (0)
; #define PG8_WAIT_V(n) asm volatile("s_waitcnt vmcnt(" #n ")" ::: "memory")
; #define PG8_BAR __builtin_amdgcn_s_barrier()
; template <class Epi, class Sched>
; __device__ __forceinline__ void gemm_phase(LAS unsigned char* lds, const int K, const int lda, const int ldb, const Sched& S, const Epi& E) {
;     ...
;         for (int t = 0; t < nt; t += 2) {
;             const bool last = (t == nt - 2);
;             const char* a1 = cA + (size_t)(t + 1) * kstep;
;             const char* a2 = last ? nA : cA + (size_t)(t + 2) * kstep; const char* b2 = last ? nB : cB + (size_t)(t + 2) * kstep;
;             const char* a3 = a2 + kstep; const char* b3 = b2 + kstep;
;             PG8_LDB(B0, 0, 0); PG8_SCHED; PG8_LDA(At, 0, 0); PG8_STAGE_A(PG8_SA(1, 1), a1, 1, vcur);
;             if constexpr (GATHER) { if (last) {
; #pragma unroll
;                 for (int h = 0; h < 2; ++h)
; #pragma unroll
;                     for (int i = 0; i < 2; ++i) vcur[h][i] = vnxt[h][i]; } }
;             PG8_WAIT_L(8); PG8_BAR; PG8_WAIT_L(0); PG8_MMA(0, 0, At, B0); PG8_BAR; PG8_SCHED;
;             PG8_LDB(B1, 0, 1); PG8_STAGE(PG8_SB(0, 0), b2, voffB);
;             PG8_BAR; PG8_WAIT_L(0); PG8_MMA(0, 1, At, B1); PG8_BAR;
;             PG8_LDA(At, 0, 1); PG8_STAGE_A(PG8_SA(0, 0), a2, 0, vcur);
;             PG8_BAR; PG8_WAIT_L(0); PG8_MMA(1, 0, At, B0); PG8_BAR; PG8_SCHED;
;             PG8_STAGE(PG8_SB(0, 1), b2 + hstepB, voffB);
;             PG8_WAIT_V(6); PG8_BAR; PG8_MMA(1, 1, At, B1); PG8_BAR;
;             PG8_LDB(B0, 1, 0); PG8_SCHED; PG8_LDA(At, 1, 0); PG8_STAGE_A(PG8_SA(0, 1), a2, 1, vcur);
;             PG8_WAIT_L(8); PG8_BAR; PG8_WAIT_L(0); PG8_MMA(0, 0, At, B0); PG8_BAR; PG8_SCHED;
;             PG8_LDB(B1, 1, 1); PG8_STAGE(PG8_SB(1, 0), b3, voffB);
;             PG8_BAR; PG8_WAIT_L(0); PG8_MMA(0, 1, At, B1); PG8_BAR;
;             PG8_LDA(At, 1, 1); PG8_STAGE_A(PG8_SA(1, 0), a3, 0, vcur);
;             PG8_BAR; PG8_WAIT_L(0); PG8_MMA(1, 0, At, B0); PG8_BAR; PG8_SCHED;
;             PG8_STAGE(PG8_SB(1, 1), b3 + hstepB, voffB);
;             PG8_WAIT_V(6); PG8_BAR; PG8_MMA(1, 1, At, B1); PG8_BAR;
	s_add_u32 s44, s12, 0x20000
	s_addc_u32 s45, s13, 0
	s_add_i32 s2, s2, s18
	v_lshl_add_u64 v[152:153], s[44:45], 0, v[0:1]
	s_mov_b32 m0, s2
	s_nop 0
	global_load_lds_dwordx4 v[152:153], off
	v_lshl_add_u64 v[152:153], s[44:45], 0, v[130:131]
	s_add_i32 m0, s2, 0x2000
	s_nop 0
	global_load_lds_dwordx4 v[152:153], off
	s_waitcnt vmcnt(6)
	s_barrier
	s_setprio 1
	v_mfma_f32_16x16x32_bf16 v[46:49], v[224:227], v[172:175], v[46:49]
	v_mfma_f32_16x16x32_bf16 v[14:17], v[232:235], v[172:175], v[14:17]
	v_mfma_f32_16x16x32_bf16 v[42:45], v[224:227], v[180:183], v[42:45]
	v_mfma_f32_16x16x32_bf16 v[10:13], v[232:235], v[180:183], v[10:13]
	v_mfma_f32_16x16x32_bf16 v[38:41], v[224:227], v[188:191], v[38:41]
	v_mfma_f32_16x16x32_bf16 v[6:9], v[232:235], v[188:191], v[6:9]
	v_mfma_f32_16x16x32_bf16 v[30:33], v[224:227], v[216:219], v[30:33]
	v_mfma_f32_16x16x32_bf16 v[2:5], v[232:235], v[216:219], v[2:5]
	v_mfma_f32_16x16x32_bf16 v[46:49], v[228:231], v[176:179], v[46:49]
	v_mfma_f32_16x16x32_bf16 v[14:17], v[236:239], v[176:179], v[14:17]
	v_mfma_f32_16x16x32_bf16 v[42:45], v[228:231], v[184:187], v[42:45]
	v_mfma_f32_16x16x32_bf16 v[10:13], v[236:239], v[184:187], v[10:13]
	v_mfma_f32_16x16x32_bf16 v[38:41], v[228:231], v[192:195], v[38:41]
	v_mfma_f32_16x16x32_bf16 v[6:9], v[236:239], v[192:195], v[6:9]
	v_mfma_f32_16x16x32_bf16 v[30:33], v[228:231], v[220:223], v[30:33]
	v_mfma_f32_16x16x32_bf16 v[2:5], v[236:239], v[220:223], v[2:5]
	s_setprio 0
	s_add_i32 s2, 0, 0x18000
	v_add_u32_e32 v163, s2, v160
	s_barrier
	ds_read_b128 v[152:155], v163
	ds_read_b128 v[156:159], v163 offset:1024
	ds_read_b128 v[164:167], v163 offset:2048
	ds_read_b128 v[168:171], v163 offset:3072
	s_add_u32 s14, s14, 0x20000
	s_addc_u32 s15, s15, 0
	s_mov_b32 m0, s34
	v_lshl_add_u64 v[224:225], s[14:15], 0, v[0:1]
	ds_read_b128 v[172:175], v162 offset:32768
	ds_read_b128 v[176:179], v162 offset:33792
	ds_read_b128 v[180:183], v162 offset:34816
	ds_read_b128 v[184:187], v162 offset:35840
	ds_read_b128 v[188:191], v162 offset:36864
	ds_read_b128 v[192:195], v162 offset:37888
	ds_read_b128 v[216:219], v162 offset:38912
	ds_read_b128 v[220:223], v162 offset:39936
	global_load_lds_dwordx4 v[224:225], off
	v_lshl_add_u64 v[224:225], s[14:15], 0, v[130:131]
	s_mov_b32 m0, s35
	s_nop 0
	global_load_lds_dwordx4 v[224:225], off
	s_waitcnt lgkmcnt(8)
	s_barrier
	s_waitcnt lgkmcnt(0)
	s_setprio 1
	s_waitcnt lgkmcnt(0)
	v_mfma_f32_16x16x32_bf16 v[126:129], v[152:155], v[172:175], v[126:129]
	v_mfma_f32_16x16x32_bf16 v[98:101], v[164:167], v[172:175], v[98:101]
	v_mfma_f32_16x16x32_bf16 v[122:125], v[152:155], v[180:183], v[122:125]
	v_mfma_f32_16x16x32_bf16 v[90:93], v[164:167], v[180:183], v[90:93]
	v_mfma_f32_16x16x32_bf16 v[118:121], v[152:155], v[188:191], v[118:121]
	v_mfma_f32_16x16x32_bf16 v[86:89], v[164:167], v[188:191], v[86:89]
	v_mfma_f32_16x16x32_bf16 v[114:117], v[152:155], v[216:219], v[114:117]
	v_mfma_f32_16x16x32_bf16 v[82:85], v[164:167], v[216:219], v[82:85]
	v_mfma_f32_16x16x32_bf16 v[126:129], v[156:159], v[176:179], v[126:129]
	v_mfma_f32_16x16x32_bf16 v[98:101], v[168:171], v[176:179], v[98:101]
	v_mfma_f32_16x16x32_bf16 v[122:125], v[156:159], v[184:187], v[122:125]
	v_mfma_f32_16x16x32_bf16 v[90:93], v[168:171], v[184:187], v[90:93]
	v_mfma_f32_16x16x32_bf16 v[118:121], v[156:159], v[192:195], v[118:121]
	v_mfma_f32_16x16x32_bf16 v[86:89], v[168:171], v[192:195], v[86:89]
	v_mfma_f32_16x16x32_bf16 v[114:117], v[156:159], v[220:223], v[114:117]
	v_mfma_f32_16x16x32_bf16 v[82:85], v[168:171], v[220:223], v[82:85]
	s_setprio 0
	s_barrier
	s_add_i32 s3, 0, 0x1c000
	s_add_i32 s2, s2, s18
	v_add_u32_e32 v163, s3, v160
	v_lshl_add_u64 v[214:215], v[214:215], 0, s[64:65]
	s_mov_b32 m0, s2
	ds_read_b128 v[224:227], v163
	ds_read_b128 v[228:231], v163 offset:1024
	ds_read_b128 v[232:235], v163 offset:2048
	ds_read_b128 v[236:239], v163 offset:3072
	global_load_lds_dwordx4 v[214:215], off
	v_lshl_add_u64 v[214:215], v[240:241], 0, s[64:65]
	s_add_i32 m0, s2, 0x2000
	s_nop 0
	global_load_lds_dwordx4 v[214:215], off
	s_barrier
	s_waitcnt lgkmcnt(0)
	s_setprio 1
	s_waitcnt lgkmcnt(0)
	v_mfma_f32_16x16x32_bf16 v[66:69], v[224:227], v[172:175], v[66:69]
	v_mfma_f32_16x16x32_bf16 v[34:37], v[232:235], v[172:175], v[34:37]
	v_mfma_f32_16x16x32_bf16 v[58:61], v[224:227], v[180:183], v[58:61]
	v_mfma_f32_16x16x32_bf16 v[26:29], v[232:235], v[180:183], v[26:29]
	v_mfma_f32_16x16x32_bf16 v[54:57], v[224:227], v[188:191], v[54:57]
	v_mfma_f32_16x16x32_bf16 v[22:25], v[232:235], v[188:191], v[22:25]
	v_mfma_f32_16x16x32_bf16 v[50:53], v[224:227], v[216:219], v[50:53]
	v_mfma_f32_16x16x32_bf16 v[18:21], v[232:235], v[216:219], v[18:21]
	v_mfma_f32_16x16x32_bf16 v[66:69], v[228:231], v[176:179], v[66:69]
	v_mfma_f32_16x16x32_bf16 v[34:37], v[236:239], v[176:179], v[34:37]
	v_mfma_f32_16x16x32_bf16 v[58:61], v[228:231], v[184:187], v[58:61]
	v_mfma_f32_16x16x32_bf16 v[26:29], v[236:239], v[184:187], v[26:29]
	v_mfma_f32_16x16x32_bf16 v[54:57], v[228:231], v[192:195], v[54:57]
	v_mfma_f32_16x16x32_bf16 v[22:25], v[236:239], v[192:195], v[22:25]
	v_mfma_f32_16x16x32_bf16 v[50:53], v[228:231], v[220:223], v[50:53]
	v_mfma_f32_16x16x32_bf16 v[18:21], v[236:239], v[220:223], v[18:21]
	s_setprio 0
	s_mov_b32 m0, s36
	v_lshl_add_u64 v[214:215], v[242:243], 0, s[64:65]
	s_barrier
	ds_read_b128 v[172:175], v162 offset:49152
	ds_read_b128 v[176:179], v162 offset:50176
	ds_read_b128 v[180:183], v162 offset:51200
	ds_read_b128 v[184:187], v162 offset:52224
	ds_read_b128 v[188:191], v162 offset:53248
	ds_read_b128 v[192:195], v162 offset:54272
	ds_read_b128 v[216:219], v162 offset:55296
	ds_read_b128 v[220:223], v162 offset:56320
	global_load_lds_dwordx4 v[214:215], off
	v_lshl_add_u64 v[214:215], v[244:245], 0, s[64:65]
	s_mov_b32 m0, s37
	s_nop 0
	global_load_lds_dwordx4 v[214:215], off
	s_barrier
; #define PG8_STAGE(bufoff, gbase, voff) do { _Pragma("unroll") for (int _i = 0; _i < 2; ++_i) \
;         __builtin_amdgcn_global_load_lds((const unsigned*)((const char*)(gbase) + (voff)[_i]), (LAS unsigned*)(lds + (bufoff) + ldsw + _i * 8192), 16, 0, 0); } while (0)
; #define PG8_STAGE_A(bufoff, gbase, h, vv) do { if constexpr (GATHER) { _Pragma("unroll") for (int _i = 0; _i < 2; ++_i) \
;         __builtin_amdgcn_global_load_lds((const unsigned*)((const char*)(gbase) + (vv)[h][_i]), (LAS unsigned*)(lds + (bufoff) + ldsw + _i * 8192), 16, 0, 0); } \
;         else { PG8_STAGE(bufoff, (gbase) + (h) * hstepA, voffA); } } while (0)
; #define PG8_WAIT_V(n) asm volatile("s_waitcnt vmcnt(" #n ")" ::: "memory")
; #define PG8_BAR __builtin_amdgcn_s_barrier()
; template <class Epi, class Sched>
; __device__ __forceinline__ void gemm_phase(LAS unsigned char* lds, const int K, const int lda, const int ldb, const Sched& S, const Epi& E) {
;     ...
;             PG8_WAIT_V(6); PG8_BAR; PG8_MMA(1, 1, At, B1); PG8_BAR;
;             PG8_LDB(B0, 1, 0); PG8_SCHED; PG8_LDA(At, 1, 0); PG8_STAGE_A(PG8_SA(0, 1), a2, 1, vcur);
;             PG8_WAIT_L(8); PG8_BAR; PG8_WAIT_L(0); PG8_MMA(0, 0, At, B0); PG8_BAR; PG8_SCHED;
;             PG8_LDB(B1, 1, 1); PG8_STAGE(PG8_SB(1, 0), b3, voffB);
;             PG8_BAR; PG8_WAIT_L(0); PG8_MMA(0, 1, At, B1); PG8_BAR;
;             PG8_LDA(At, 1, 1); PG8_STAGE_A(PG8_SA(1, 0), a3, 0, vcur);
;             PG8_BAR; PG8_WAIT_L(0); PG8_MMA(1, 0, At, B0); PG8_BAR; PG8_SCHED;
;             PG8_STAGE(PG8_SB(1, 1), b3 + hstepB, voffB);
;             PG8_WAIT_V(6); PG8_BAR; PG8_MMA(1, 1, At, B1); PG8_BAR;
;         }
;     __device__ __forceinline__ void operator()(const Acc& acc, const Unit& u, int wr, int wc, int fr, int fq) const {
;         const int row0 = wr * 64 + fr, col0 = u.pn * BM + wc * 32 + 4 * fq;
; #pragma unroll
;         for (int bj = 0; bj < 2; ++bj)
; #pragma unroll
;             for (int n = 0; n < 2; ++n) { const int col = col0 + bj * HALF + n * 16;
;                 const f32x4 g = *(const f32x4*)(gate + col) * (1.f / 256.f);
; #pragma unroll
;                 for (int ai = 0; ai < 2; ++ai)
; #pragma unroll
;                     for (int m = 0; m < 4; ++m) { f32x4* p = (f32x4*)(X + (size_t)(SEQ + row0 + ai * HALF + m * 16) * D + col); *p = *p + g * acc[ai][bj][m][n]; }
;                 __builtin_amdgcn_sched_barrier(0); }
	s_waitcnt lgkmcnt(0)
	s_setprio 1
	s_waitcnt lgkmcnt(0)
	v_mfma_f32_16x16x32_bf16 v[110:113], v[152:155], v[172:175], v[110:113]
	v_mfma_f32_16x16x32_bf16 v[78:81], v[164:167], v[172:175], v[78:81]
	v_mfma_f32_16x16x32_bf16 v[106:109], v[152:155], v[180:183], v[106:109]
	v_mfma_f32_16x16x32_bf16 v[74:77], v[164:167], v[180:183], v[74:77]
	v_mfma_f32_16x16x32_bf16 v[102:105], v[152:155], v[188:191], v[102:105]
	v_mfma_f32_16x16x32_bf16 v[70:73], v[164:167], v[188:191], v[70:73]
	v_mfma_f32_16x16x32_bf16 v[94:97], v[152:155], v[216:219], v[94:97]
	v_mfma_f32_16x16x32_bf16 v[62:65], v[164:167], v[216:219], v[62:65]
	v_mfma_f32_16x16x32_bf16 v[110:113], v[156:159], v[176:179], v[110:113]
	v_mfma_f32_16x16x32_bf16 v[78:81], v[168:171], v[176:179], v[78:81]
	v_mfma_f32_16x16x32_bf16 v[106:109], v[156:159], v[184:187], v[106:109]
	v_mfma_f32_16x16x32_bf16 v[74:77], v[168:171], v[184:187], v[74:77]
	v_mfma_f32_16x16x32_bf16 v[102:105], v[156:159], v[192:195], v[102:105]
	v_mfma_f32_16x16x32_bf16 v[70:73], v[168:171], v[192:195], v[70:73]
	v_mfma_f32_16x16x32_bf16 v[94:97], v[156:159], v[220:223], v[94:97]
	v_mfma_f32_16x16x32_bf16 v[62:65], v[168:171], v[220:223], v[62:65]
	s_setprio 0
	s_barrier
	s_add_u32 s12, s12, 0x20080
	s_addc_u32 s13, s13, 0
	s_add_i32 s2, s3, s18
	v_lshl_add_u64 v[152:153], s[12:13], 0, v[0:1]
	s_mov_b32 m0, s2
	s_nop 0
	global_load_lds_dwordx4 v[152:153], off
	v_lshl_add_u64 v[152:153], s[12:13], 0, v[130:131]
	s_add_i32 m0, s2, 0x2000
	s_nop 0
	global_load_lds_dwordx4 v[152:153], off
	s_waitcnt vmcnt(6)
	s_barrier
	s_setprio 1
	v_mfma_f32_16x16x32_bf16 v[46:49], v[224:227], v[172:175], v[46:49]
	v_mfma_f32_16x16x32_bf16 v[14:17], v[232:235], v[172:175], v[14:17]
	v_mfma_f32_16x16x32_bf16 v[42:45], v[224:227], v[180:183], v[42:45]
	v_mfma_f32_16x16x32_bf16 v[10:13], v[232:235], v[180:183], v[10:13]
	v_mfma_f32_16x16x32_bf16 v[38:41], v[224:227], v[188:191], v[38:41]
	v_mfma_f32_16x16x32_bf16 v[6:9], v[232:235], v[188:191], v[6:9]
	v_mfma_f32_16x16x32_bf16 v[30:33], v[224:227], v[216:219], v[30:33]
	v_mfma_f32_16x16x32_bf16 v[2:5], v[232:235], v[216:219], v[2:5]
	v_mfma_f32_16x16x32_bf16 v[46:49], v[228:231], v[176:179], v[46:49]
	v_mfma_f32_16x16x32_bf16 v[14:17], v[236:239], v[176:179], v[14:17]
	v_mfma_f32_16x16x32_bf16 v[42:45], v[228:231], v[184:187], v[42:45]
	v_mfma_f32_16x16x32_bf16 v[10:13], v[236:239], v[184:187], v[10:13]
	v_mfma_f32_16x16x32_bf16 v[38:41], v[228:231], v[192:195], v[38:41]
	v_mfma_f32_16x16x32_bf16 v[6:9], v[236:239], v[192:195], v[6:9]
	v_mfma_f32_16x16x32_bf16 v[30:33], v[228:231], v[220:223], v[30:33]
	v_mfma_f32_16x16x32_bf16 v[2:5], v[236:239], v[220:223], v[2:5]
	s_setprio 0
	s_add_i32 s43, s43, 2
	s_add_u32 s10, s10, 0x100
	s_addc_u32 s11, s11, 0
	s_add_u32 s41, s41, 0x100
	s_addc_u32 s42, s42, 0
	s_cmp_gt_u32 s43, 5
	s_barrier
	s_cbranch_scc0 .LBB0_270
	v_lshl_or_b32 v154, s40, 8, v161
	v_ashrrev_i32_e32 v155, 31, v154
	v_lshlrev_b64 v[168:169], 2, v[154:155]
	v_lshl_add_u64 v[152:153], s[0:1], 0, v[168:169]
	global_load_dwordx4 v[164:167], v[152:153], off
	s_mov_b32 s2, 0x3b800000
	v_lshl_add_u64 v[152:153], v[132:133], 0, v[168:169]
	s_waitcnt vmcnt(0)
	v_pk_mul_f32 v[156:157], v[166:167], s[2:3] op_sel_hi:[1,0]
	v_pk_mul_f32 v[158:159], v[164:165], s[2:3] op_sel_hi:[1,0]
	global_load_dwordx4 v[172:175], v[152:153], off
	v_lshl_add_u64 v[224:225], v[134:135], 0, v[168:169]
	global_load_dwordx4 v[176:179], v[224:225], off
	v_lshl_add_u64 v[224:225], v[136:137], 0, v[168:169]
	global_load_dwordx4 v[180:183], v[224:225], off
	v_lshl_add_u64 v[224:225], v[138:139], 0, v[168:169]
	global_load_dwordx4 v[184:187], v[224:225], off
	v_lshl_add_u64 v[224:225], v[140:141], 0, v[168:169]
	global_load_dwordx4 v[188:191], v[224:225], off
	v_lshl_add_u64 v[224:225], v[142:143], 0, v[168:169]
	global_load_dwordx4 v[192:195], v[224:225], off
	v_lshl_add_u64 v[224:225], v[144:145], 0, v[168:169]
	global_load_dwordx4 v[216:219], v[224:225], off
	v_lshl_add_u64 v[224:225], v[146:147], 0, v[168:169]
	global_load_dwordx4 v[220:223], v[224:225], off
	s_waitcnt vmcnt(7)
	v_pk_fma_f32 v[128:129], v[128:129], v[156:157], v[174:175]
	v_pk_fma_f32 v[126:127], v[126:127], v[158:159], v[172:173]
	global_store_dwordx4 v[152:153], v[126:129], off
	s_nop 1
	v_lshl_add_u64 v[126:127], v[134:135], 0, v[168:169]
	s_waitcnt vmcnt(7)
	v_pk_fma_f32 v[124:125], v[124:125], v[156:157], v[178:179]
	v_pk_fma_f32 v[122:123], v[122:123], v[158:159], v[176:177]
	global_store_dwordx4 v[126:127], v[122:125], off
	s_nop 1
	v_lshl_add_u64 v[122:123], v[136:137], 0, v[168:169]
	s_waitcnt vmcnt(7)
	v_pk_fma_f32 v[120:121], v[120:121], v[156:157], v[182:183]
	v_pk_fma_f32 v[118:119], v[118:119], v[158:159], v[180:181]
	global_store_dwordx4 v[122:123], v[118:121], off
	s_nop 1
	v_lshl_add_u64 v[118:119], v[138:139], 0, v[168:169]
	s_waitcnt vmcnt(7)
	v_pk_fma_f32 v[116:117], v[116:117], v[156:157], v[186:187]
	v_pk_fma_f32 v[114:115], v[114:115], v[158:159], v[184:185]
	global_store_dwordx4 v[118:119], v[114:117], off
	s_nop 1
	v_lshl_add_u64 v[114:115], v[140:141], 0, v[168:169]
	s_waitcnt vmcnt(7)
	v_pk_fma_f32 v[112:113], v[112:113], v[156:157], v[190:191]
	v_pk_fma_f32 v[110:111], v[110:111], v[158:159], v[188:189]
	global_store_dwordx4 v[114:115], v[110:113], off
	s_nop 1
	v_lshl_add_u64 v[110:111], v[142:143], 0, v[168:169]
	s_waitcnt vmcnt(7)
	v_pk_fma_f32 v[108:109], v[108:109], v[156:157], v[194:195]
	v_pk_fma_f32 v[106:107], v[106:107], v[158:159], v[192:193]
	global_store_dwordx4 v[110:111], v[106:109], off
	s_nop 1
	v_lshl_add_u64 v[106:107], v[144:145], 0, v[168:169]
	s_waitcnt vmcnt(7)
;     __device__ __forceinline__ void operator()(const Acc& acc, const Unit& u, int wr, int wc, int fr, int fq) const {
;     ...
;         for (int bj = 0; bj < 2; ++bj)
; #pragma unroll
;             for (int n = 0; n < 2; ++n) { const int col = col0 + bj * HALF + n * 16;
;                 const f32x4 g = *(const f32x4*)(gate + col) * (1.f / 256.f);
; #pragma unroll
;                 for (int ai = 0; ai < 2; ++ai)
; #pragma unroll
;                     for (int m = 0; m < 4; ++m) { f32x4* p = (f32x4*)(X + (size_t)(SEQ + row0 + ai * HALF + m * 16) * D + col); *p = *p + g * acc[ai][bj][m][n]; }
;                 __builtin_amdgcn_sched_barrier(0); }
	v_pk_fma_f32 v[104:105], v[104:105], v[156:157], v[218:219]
	v_pk_fma_f32 v[102:103], v[102:103], v[158:159], v[216:217]
	global_store_dwordx4 v[106:107], v[102:105], off
	s_nop 1
	v_lshl_add_u64 v[102:103], v[146:147], 0, v[168:169]
	s_waitcnt vmcnt(7)
	v_pk_fma_f32 v[96:97], v[96:97], v[156:157], v[222:223]
	v_pk_fma_f32 v[94:95], v[94:95], v[158:159], v[220:221]
	global_store_dwordx4 v[102:103], v[94:97], off
	s_nop 1
	v_or_b32_e32 v94, 16, v154
	v_ashrrev_i32_e32 v95, 31, v94
	v_lshl_add_u64 v[94:95], v[94:95], 2, s[0:1]
	global_load_dwordx4 v[94:97], v[94:95], off
	s_waitcnt vmcnt(0)
	v_pk_mul_f32 v[104:105], v[96:97], s[2:3] op_sel_hi:[1,0]
	v_pk_mul_f32 v[108:109], v[94:95], s[2:3] op_sel_hi:[1,0]
	global_load_dwordx4 v[172:175], v[152:153], off offset:64
	global_load_dwordx4 v[176:179], v[126:127], off offset:64
	global_load_dwordx4 v[180:183], v[122:123], off offset:64
	global_load_dwordx4 v[184:187], v[118:119], off offset:64
	global_load_dwordx4 v[188:191], v[114:115], off offset:64
	global_load_dwordx4 v[192:195], v[110:111], off offset:64
	global_load_dwordx4 v[216:219], v[106:107], off offset:64
	global_load_dwordx4 v[220:223], v[102:103], off offset:64
	s_waitcnt vmcnt(7)
	v_pk_fma_f32 v[96:97], v[100:101], v[104:105], v[174:175]
	v_pk_fma_f32 v[94:95], v[98:99], v[108:109], v[172:173]
	global_store_dwordx4 v[152:153], v[94:97], off offset:64
	s_waitcnt vmcnt(7)
	v_pk_fma_f32 v[92:93], v[92:93], v[104:105], v[178:179]
	v_pk_fma_f32 v[90:91], v[90:91], v[108:109], v[176:177]
	global_store_dwordx4 v[126:127], v[90:93], off offset:64
	s_waitcnt vmcnt(7)
	v_pk_fma_f32 v[88:89], v[88:89], v[104:105], v[182:183]
	v_pk_fma_f32 v[86:87], v[86:87], v[108:109], v[180:181]
	global_store_dwordx4 v[122:123], v[86:89], off offset:64
	s_waitcnt vmcnt(7)
	v_pk_fma_f32 v[84:85], v[84:85], v[104:105], v[186:187]
	v_pk_fma_f32 v[82:83], v[82:83], v[108:109], v[184:185]
	global_store_dwordx4 v[118:119], v[82:85], off offset:64
	s_waitcnt vmcnt(7)
	v_pk_fma_f32 v[80:81], v[80:81], v[104:105], v[190:191]
	v_pk_fma_f32 v[78:79], v[78:79], v[108:109], v[188:189]
	global_store_dwordx4 v[114:115], v[78:81], off offset:64
	s_waitcnt vmcnt(7)
	v_pk_fma_f32 v[76:77], v[76:77], v[104:105], v[194:195]
	v_pk_fma_f32 v[74:75], v[74:75], v[108:109], v[192:193]
	global_store_dwordx4 v[110:111], v[74:77], off offset:64
	s_waitcnt vmcnt(7)
	v_pk_fma_f32 v[72:73], v[72:73], v[104:105], v[218:219]
	v_pk_fma_f32 v[70:71], v[70:71], v[108:109], v[216:217]
	global_store_dwordx4 v[106:107], v[70:73], off offset:64
	s_waitcnt vmcnt(7)
	v_pk_fma_f32 v[64:65], v[64:65], v[104:105], v[222:223]
	v_pk_fma_f32 v[62:63], v[62:63], v[108:109], v[220:221]
	global_store_dwordx4 v[102:103], v[62:65], off offset:64
	s_nop 1
	v_or_b32_e32 v62, 0x80, v154
	v_ashrrev_i32_e32 v63, 31, v62
	v_lshl_add_u64 v[62:63], v[62:63], 2, s[0:1]
	global_load_dwordx4 v[62:65], v[62:63], off
	s_waitcnt vmcnt(0)
	v_pk_mul_f32 v[70:71], v[64:65], s[2:3] op_sel_hi:[1,0]
	v_pk_mul_f32 v[72:73], v[62:63], s[2:3] op_sel_hi:[1,0]
	global_load_dwordx4 v[172:175], v[152:153], off offset:512
	global_load_dwordx4 v[176:179], v[126:127], off offset:512
	global_load_dwordx4 v[180:183], v[122:123], off offset:512
	global_load_dwordx4 v[184:187], v[118:119], off offset:512
	global_load_dwordx4 v[188:191], v[114:115], off offset:512
	global_load_dwordx4 v[192:195], v[110:111], off offset:512
	global_load_dwordx4 v[216:219], v[106:107], off offset:512
	global_load_dwordx4 v[220:223], v[102:103], off offset:512
	s_waitcnt vmcnt(7)
	v_pk_fma_f32 v[64:65], v[68:69], v[70:71], v[174:175]
	v_pk_fma_f32 v[62:63], v[66:67], v[72:73], v[172:173]
	global_store_dwordx4 v[152:153], v[62:65], off offset:512
	s_waitcnt vmcnt(7)
; #define PG8_WAIT_V(n) asm volatile("s_waitcnt vmcnt(" #n ")" ::: "memory")
; #define PG8_BAR __builtin_amdgcn_s_barrier()
; template <class Epi, class Sched>
; __device__ __forceinline__ void gemm_phase(LAS unsigned char* lds, const int K, const int lda, const int ldb, const Sched& S, const Epi& E) {
;     ...
;         if constexpr (!Epi::AFTER_DRAIN) E(acc, cur, wr, wc, fr, fq);
;         if (!has_next) break;
; #pragma unroll
;         for (int a = 0; a < 2; ++a)
; #pragma unroll
;             for (int b = 0; b < 2; ++b)
; #pragma unroll
;                 for (int m = 0; m < 4; ++m)
; #pragma unroll
;                     for (int n = 0; n < 2; ++n) acc[a][b][m][n] = (f32x4){0.f, 0.f, 0.f, 0.f};
;         cur = nxt; cA = nA; cB = nB; ++ui;
;     }
;     PG8_WAIT_V(0);
;     if (wr == 0) PG8_BAR;
;     PG8_BAR;
;     __device__ __forceinline__ void operator()(const Acc& acc, const Unit& u, int wr, int wc, int fr, int fq) const {
;     ...
;         for (int bj = 0; bj < 2; ++bj)
; #pragma unroll
;             for (int n = 0; n < 2; ++n) { const int col = col0 + bj * HALF + n * 16;
;                 const f32x4 g = *(const f32x4*)(gate + col) * (1.f / 256.f);
; #pragma unroll
;                 for (int ai = 0; ai < 2; ++ai)
; #pragma unroll
;                     for (int m = 0; m < 4; ++m) { f32x4* p = (f32x4*)(X + (size_t)(SEQ + row0 + ai * HALF + m * 16) * D + col); *p = *p + g * acc[ai][bj][m][n]; }
;                 __builtin_amdgcn_sched_barrier(0); }
	v_pk_fma_f32 v[60:61], v[60:61], v[70:71], v[178:179]
	v_pk_fma_f32 v[58:59], v[58:59], v[72:73], v[176:177]
	global_store_dwordx4 v[126:127], v[58:61], off offset:512
	s_waitcnt vmcnt(7)
	v_pk_fma_f32 v[56:57], v[56:57], v[70:71], v[182:183]
	v_pk_fma_f32 v[54:55], v[54:55], v[72:73], v[180:181]
	global_store_dwordx4 v[122:123], v[54:57], off offset:512
	s_waitcnt vmcnt(7)
	v_pk_fma_f32 v[52:53], v[52:53], v[70:71], v[186:187]
	v_pk_fma_f32 v[50:51], v[50:51], v[72:73], v[184:185]
	global_store_dwordx4 v[118:119], v[50:53], off offset:512
	s_waitcnt vmcnt(7)
	v_pk_fma_f32 v[48:49], v[48:49], v[70:71], v[190:191]
	v_pk_fma_f32 v[46:47], v[46:47], v[72:73], v[188:189]
	global_store_dwordx4 v[114:115], v[46:49], off offset:512
	s_waitcnt vmcnt(7)
	v_pk_fma_f32 v[44:45], v[44:45], v[70:71], v[194:195]
	v_pk_fma_f32 v[42:43], v[42:43], v[72:73], v[192:193]
	global_store_dwordx4 v[110:111], v[42:45], off offset:512
	s_waitcnt vmcnt(7)
	v_pk_fma_f32 v[40:41], v[40:41], v[70:71], v[218:219]
	v_pk_fma_f32 v[38:39], v[38:39], v[72:73], v[216:217]
	global_store_dwordx4 v[106:107], v[38:41], off offset:512
	s_waitcnt vmcnt(7)
	v_pk_fma_f32 v[32:33], v[32:33], v[70:71], v[222:223]
	v_pk_fma_f32 v[30:31], v[30:31], v[72:73], v[220:221]
	global_store_dwordx4 v[102:103], v[30:33], off offset:512
	s_nop 1
	v_or_b32_e32 v30, 0x90, v154
	v_ashrrev_i32_e32 v31, 31, v30
	v_lshl_add_u64 v[30:31], v[30:31], 2, s[0:1]
	global_load_dwordx4 v[30:33], v[30:31], off
	s_waitcnt vmcnt(0)
	v_pk_mul_f32 v[38:39], v[32:33], s[2:3] op_sel_hi:[1,0]
	v_pk_mul_f32 v[40:41], v[30:31], s[2:3] op_sel_hi:[1,0]
	global_load_dwordx4 v[172:175], v[152:153], off offset:576
	global_load_dwordx4 v[176:179], v[126:127], off offset:576
	global_load_dwordx4 v[180:183], v[122:123], off offset:576
	global_load_dwordx4 v[184:187], v[118:119], off offset:576
	global_load_dwordx4 v[188:191], v[114:115], off offset:576
	global_load_dwordx4 v[192:195], v[110:111], off offset:576
	global_load_dwordx4 v[216:219], v[106:107], off offset:576
	global_load_dwordx4 v[220:223], v[102:103], off offset:576
	s_waitcnt vmcnt(7)
	v_pk_fma_f32 v[32:33], v[36:37], v[38:39], v[174:175]
	v_pk_fma_f32 v[30:31], v[34:35], v[40:41], v[172:173]
	global_store_dwordx4 v[152:153], v[30:33], off offset:576
	s_waitcnt vmcnt(7)
	v_pk_fma_f32 v[28:29], v[28:29], v[38:39], v[178:179]
	v_pk_fma_f32 v[26:27], v[26:27], v[40:41], v[176:177]
	global_store_dwordx4 v[126:127], v[26:29], off offset:576
	s_waitcnt vmcnt(7)
	v_pk_fma_f32 v[24:25], v[24:25], v[38:39], v[182:183]
	v_pk_fma_f32 v[22:23], v[22:23], v[40:41], v[180:181]
	global_store_dwordx4 v[122:123], v[22:25], off offset:576
	s_waitcnt vmcnt(7)
	v_pk_fma_f32 v[20:21], v[20:21], v[38:39], v[186:187]
	v_pk_fma_f32 v[18:19], v[18:19], v[40:41], v[184:185]
	global_store_dwordx4 v[118:119], v[18:21], off offset:576
	s_waitcnt vmcnt(7)
	v_pk_fma_f32 v[16:17], v[16:17], v[38:39], v[190:191]
	v_pk_fma_f32 v[14:15], v[14:15], v[40:41], v[188:189]
	global_store_dwordx4 v[114:115], v[14:17], off offset:576
	s_waitcnt vmcnt(7)
	v_pk_fma_f32 v[12:13], v[12:13], v[38:39], v[194:195]
	v_pk_fma_f32 v[10:11], v[10:11], v[40:41], v[192:193]
	global_store_dwordx4 v[110:111], v[10:13], off offset:576
	s_waitcnt vmcnt(7)
	v_pk_fma_f32 v[8:9], v[8:9], v[38:39], v[218:219]
	v_pk_fma_f32 v[6:7], v[6:7], v[40:41], v[216:217]
	global_store_dwordx4 v[106:107], v[6:9], off offset:576
	s_waitcnt vmcnt(7)
	v_pk_fma_f32 v[4:5], v[4:5], v[38:39], v[222:223]
	v_pk_fma_f32 v[2:3], v[2:3], v[40:41], v[220:221]
	global_store_dwordx4 v[102:103], v[2:5], off offset:576
	s_and_b64 vcc, exec, s[4:5]
	s_mov_b32 s40, s39
	s_mov_b64 s[12:13], s[8:9]
	s_mov_b64 s[10:11], s[6:7]
	s_cbranch_vccz .LBB0_267
	s_waitcnt vmcnt(0)
	s_cmpk_gt_u32 s17, 0xff
	s_cbranch_scc1 .LBB0_274
	s_barrier
